# P9 context half-tile GEMM (layer-0 tail, one workgroup per CU): all 12 fragment reads of a k-chunk issued up front with counted waits instead of one lgkmcnt(0) per MFMA
# speedup vs baseline: 1.0038x; 1.0038x over previous
; #define MFMA32(a, b, c) __builtin_amdgcn_mfma_f32_32x32x16_bf16((a), (b), (c), 0, 0, 0)
; #define GEMM_LOADG(kk) { const int ka_ = amode ? (((kk) >> 6) * 96) : (kk); \
;     _Pragma("unroll") for (int i = 0; i < 4; ++i) ra[i] = *(const u32x4*)(A + (size_t)(lr + 32 * i) * lda + ka_ + lk); \
;     _Pragma("unroll") for (int i = 0; i < 2 * NT; ++i) rb[i] = *(const u32x4*)(Bt + (size_t)(lr + 32 * i) * ldb + (kk) + lk); }
; #define GEMM_STORES(buf) { u16* As_ = S + (buf) * TILE; u16* Bs_ = As_ + 128 * LS; \
;     _Pragma("unroll") for (int i = 0; i < 4; ++i) *(u32x4*)(As_ + (lr + 32 * i) * LS + lk) = ra[i]; \
;     _Pragma("unroll") for (int i = 0; i < 2 * NT; ++i) *(u32x4*)(Bs_ + (lr + 32 * i) * LS + lk) = rb[i]; }
; template <int NT>
; DI void gemm_main_np(f32x16 (&acc)[2][NT], const u16* __restrict__ A, int lda, int amode, const u16* __restrict__ Bt,
;                   int ldb, int K, char* smem) {
;     ...
;   for (int k0 = 0; k0 < K; k0 += 64) {
;     const int cur = (k0 >> 6) & 1;
;     if (k0 + 64 < K) {
;       GEMM_STORES(cur ^ 1)
;       if (k0 + 128 < K) GEMM_LOADG(k0 + 128)
;     }
;     const u16* As = S + cur * TILE;
;     const u16* Bs = As + 128 * LS;
; #pragma unroll
;     for (int s = 0; s < 4; ++s) {
;       bf16x8 a[2], b[NT];
; #pragma unroll
;       for (int i = 0; i < 2; ++i) a[i] = *(const bf16x8*)(As + (wm * 64 + i * 32 + l31) * LS + s * 16 + hh * 8);
; #pragma unroll
;       for (int j = 0; j < NT; ++j) b[j] = *(const bf16x8*)(Bs + (wn * 32 * NT + j * 32 + l31) * LS + s * 16 + hh * 8);
; #pragma unroll
;       for (int i = 0; i < 2; ++i)
; #pragma unroll
;         for (int j = 0; j < NT; ++j) acc[i][j] = MFMA32(a[i], b[j], acc[i][j]);
;     }
;     __syncthreads();
.LBB0_2009:
	ds_read_b128 v[132:135], v65 offset:27648
	ds_read_b128 v[136:139], v66 offset:46080
	ds_read_b128 v[140:143], v65 offset:32256
	ds_read_b128 v[144:147], v65 offset:27680
	ds_read_b128 v[148:151], v66 offset:46112
	ds_read_b128 v[152:155], v65 offset:32288
	ds_read_b128 v[156:159], v65 offset:27712
	ds_read_b128 v[160:163], v66 offset:46144
	ds_read_b128 v[164:167], v65 offset:32320
	ds_read_b128 v[168:171], v65 offset:27744
	ds_read_b128 v[172:175], v66 offset:46176
	ds_read_b128 v[176:179], v65 offset:32352
	s_mov_b64 s[16:17], 0x100
	v_lshl_add_u64 v[58:59], v[58:59], 0, s[16:17]
	v_lshl_add_u64 v[60:61], v[60:61], 0, s[16:17]
	s_andn2_b64 vcc, exec, s[10:11]
	s_waitcnt lgkmcnt(11)
	s_waitcnt lgkmcnt(10)
	v_mfma_f32_32x32x16_bf16 v[18:33], v[132:135], v[136:139], v[18:33]
	s_waitcnt lgkmcnt(9)
	v_mfma_f32_32x32x16_bf16 v[2:17], v[140:143], v[136:139], v[2:17]
	s_waitcnt lgkmcnt(8)
	s_waitcnt lgkmcnt(7)
	v_mfma_f32_32x32x16_bf16 v[18:33], v[144:147], v[148:151], v[18:33]
	s_waitcnt lgkmcnt(6)
	v_mfma_f32_32x32x16_bf16 v[2:17], v[152:155], v[148:151], v[2:17]
	s_waitcnt lgkmcnt(5)
	s_waitcnt lgkmcnt(4)
	v_mfma_f32_32x32x16_bf16 v[18:33], v[156:159], v[160:163], v[18:33]
	s_waitcnt lgkmcnt(3)
	v_mfma_f32_32x32x16_bf16 v[2:17], v[164:167], v[160:163], v[2:17]
	s_waitcnt lgkmcnt(0)
	s_barrier
	v_mfma_f32_32x32x16_bf16 v[18:33], v[168:171], v[172:175], v[18:33]
	v_mfma_f32_32x32x16_bf16 v[2:17], v[176:179], v[172:175], v[2:17]
	s_cbranch_vccz .LBB0_2015

; #define MFMA32(a, b, c) __builtin_amdgcn_mfma_f32_32x32x16_bf16((a), (b), (c), 0, 0, 0)
; #define GEMM_LOADG(kk) { const int ka_ = amode ? (((kk) >> 6) * 96) : (kk); \
;     _Pragma("unroll") for (int i = 0; i < 4; ++i) ra[i] = *(const u32x4*)(A + (size_t)(lr + 32 * i) * lda + ka_ + lk); \
;     _Pragma("unroll") for (int i = 0; i < 2 * NT; ++i) rb[i] = *(const u32x4*)(Bt + (size_t)(lr + 32 * i) * ldb + (kk) + lk); }
; #define GEMM_STORES(buf) { u16* As_ = S + (buf) * TILE; u16* Bs_ = As_ + 128 * LS; \
;     _Pragma("unroll") for (int i = 0; i < 4; ++i) *(u32x4*)(As_ + (lr + 32 * i) * LS + lk) = ra[i]; \
;     _Pragma("unroll") for (int i = 0; i < 2 * NT; ++i) *(u32x4*)(Bs_ + (lr + 32 * i) * LS + lk) = rb[i]; }
; template <int NT>
; DI void gemm_main_np(f32x16 (&acc)[2][NT], const u16* __restrict__ A, int lda, int amode, const u16* __restrict__ Bt,
;                   int ldb, int K, char* smem) {
;     ...
;   for (int k0 = 0; k0 < K; k0 += 64) {
;     const int cur = (k0 >> 6) & 1;
;     if (k0 + 64 < K) {
;       GEMM_STORES(cur ^ 1)
;       if (k0 + 128 < K) GEMM_LOADG(k0 + 128)
;     }
;     const u16* As = S + cur * TILE;
;     const u16* Bs = As + 128 * LS;
; #pragma unroll
;     for (int s = 0; s < 4; ++s) {
;       bf16x8 a[2], b[NT];
; #pragma unroll
;       for (int i = 0; i < 2; ++i) a[i] = *(const bf16x8*)(As + (wm * 64 + i * 32 + l31) * LS + s * 16 + hh * 8);
; #pragma unroll
;       for (int j = 0; j < NT; ++j) b[j] = *(const bf16x8*)(Bs + (wn * 32 * NT + j * 32 + l31) * LS + s * 16 + hh * 8);
; #pragma unroll
;       for (int i = 0; i < 2; ++i)
; #pragma unroll
;         for (int j = 0; j < NT; ++j) acc[i][j] = MFMA32(a[i], b[j], acc[i][j]);
;     }
;     __syncthreads();
.LBB0_2012:
	ds_read_b128 v[132:135], v65
	ds_read_b128 v[136:139], v66 offset:18432
	ds_read_b128 v[140:143], v65 offset:4608
	ds_read_b128 v[144:147], v65 offset:32
	ds_read_b128 v[148:151], v66 offset:18464
	ds_read_b128 v[152:155], v65 offset:4640
	ds_read_b128 v[156:159], v65 offset:64
	ds_read_b128 v[160:163], v66 offset:18496
	ds_read_b128 v[164:167], v65 offset:4672
	ds_read_b128 v[168:171], v65 offset:96
	ds_read_b128 v[172:175], v66 offset:18528
	ds_read_b128 v[176:179], v65 offset:4704
	s_addk_i32 s4, 0x80
	s_cmpk_gt_u32 s4, 0xabf
	s_cselect_b64 s[10:11], -1, 0
	s_and_b64 vcc, exec, s[10:11]
	s_waitcnt lgkmcnt(11)
	s_waitcnt lgkmcnt(10)
	v_mfma_f32_32x32x16_bf16 v[18:33], v[132:135], v[136:139], v[18:33]
	s_waitcnt lgkmcnt(9)
	v_mfma_f32_32x32x16_bf16 v[2:17], v[140:143], v[136:139], v[2:17]
	s_waitcnt lgkmcnt(8)
	s_waitcnt lgkmcnt(7)
	v_mfma_f32_32x32x16_bf16 v[18:33], v[144:147], v[148:151], v[18:33]
	s_waitcnt lgkmcnt(6)
	v_mfma_f32_32x32x16_bf16 v[2:17], v[152:155], v[148:151], v[2:17]
	s_waitcnt lgkmcnt(5)
	s_waitcnt lgkmcnt(4)
	v_mfma_f32_32x32x16_bf16 v[18:33], v[156:159], v[160:163], v[18:33]
	s_waitcnt lgkmcnt(3)
	v_mfma_f32_32x32x16_bf16 v[2:17], v[164:167], v[160:163], v[2:17]
	s_waitcnt lgkmcnt(0)
	s_barrier
	v_mfma_f32_32x32x16_bf16 v[18:33], v[168:171], v[172:175], v[18:33]
	v_mfma_f32_32x32x16_bf16 v[2:17], v[176:179], v[172:175], v[2:17]
	s_cbranch_vccnz .LBB0_2009
	s_andn2_b64 vcc, exec, s[16:17]
	s_waitcnt vmcnt(5)
	ds_write_b128 v64, v[34:37]
	s_waitcnt vmcnt(4)
	ds_write_b128 v64, v[38:41] offset:4608
	s_waitcnt vmcnt(3)
	ds_write_b128 v64, v[42:45] offset:9216
	s_waitcnt vmcnt(2)
	ds_write_b128 v64, v[46:49] offset:13824
	s_waitcnt vmcnt(1)
	ds_write_b128 v64, v[50:53] offset:18432
	s_waitcnt vmcnt(0)
	ds_write_b128 v64, v[54:57] offset:23040
	s_cbranch_vccnz .LBB0_2009
	v_lshl_add_u64 v[42:43], v[60:61], 0, v[198:199]
	v_add_co_u32_e32 v34, vcc, 0x7a00000, v42
	v_lshl_add_u64 v[50:51], v[58:59], 0, v[198:199]
	s_nop 0
	v_addc_co_u32_e32 v35, vcc, 0, v43, vcc
	v_add_co_u32_e32 v38, vcc, 0x7a2c000, v42
	s_nop 1
	v_addc_co_u32_e32 v39, vcc, 0, v43, vcc
	v_add_co_u32_e32 v44, vcc, 0x7a58000, v42
	global_load_dwordx4 v[34:37], v[34:35], off offset:384
	s_nop 0
	global_load_dwordx4 v[38:41], v[38:39], off offset:384
	v_addc_co_u32_e32 v45, vcc, 0, v43, vcc
	v_add_co_u32_e32 v46, vcc, 0x7a84000, v42
	s_nop 1
	v_addc_co_u32_e32 v47, vcc, 0, v43, vcc
	v_add_co_u32_e32 v52, vcc, 0xdc50000, v50
	global_load_dwordx4 v[42:45], v[44:45], off offset:384
	s_nop 0
	global_load_dwordx4 v[46:49], v[46:47], off offset:384
	v_addc_co_u32_e32 v53, vcc, 0, v51, vcc
	v_add_co_u32_e32 v54, vcc, 0xdc7c000, v50
	s_nop 1
	v_addc_co_u32_e32 v55, vcc, 0, v51, vcc
	global_load_dwordx4 v[50:53], v[52:53], off offset:384
	s_nop 0
	global_load_dwordx4 v[54:57], v[54:55], off offset:384
	s_branch .LBB0_2009
